# v63 + windowed-attention unit boundary: next unit's sink value loaded in the epilogue, wait for DMA/Q/sink in front of the output stores, header barrier waits on LDS only
# baseline (speedup 1.0000x reference)
.LBB0_1338:
	s_abs_i32 s0, s33
	v_cvt_f32_u32_e32 v1, s0
	s_sub_i32 s5, 0, s0
	s_add_i32 s1, s33, 0x3ff
	s_xor_b32 s4, s1, s33
	v_rcp_iflag_f32_e32 v1, v1
	s_abs_i32 s1, s1
	s_ashr_i32 s4, s4, 31
	v_mul_f32_e32 v1, 0x4f7ffffe, v1
	v_cvt_u32_f32_e32 v1, v1
	s_nop 0
	v_readfirstlane_b32 s6, v1
	s_mul_i32 s5, s5, s6
	s_mul_hi_u32 s5, s6, s5
	s_add_i32 s6, s6, s5
	s_mul_hi_u32 s5, s1, s6
	s_mul_i32 s6, s5, s0
	s_sub_i32 s1, s1, s6
	s_add_i32 s7, s5, 1
	s_sub_i32 s6, s1, s0
	s_cmp_ge_u32 s1, s0
	s_cselect_b32 s5, s7, s5
	s_cselect_b32 s1, s6, s1
	s_add_i32 s6, s5, 1
	s_cmp_ge_u32 s1, s0
	s_cselect_b32 s0, s6, s5
	s_xor_b32 s0, s0, s4
	s_sub_i32 s0, s0, s4
	s_mul_i32 s52, s0, s87
	s_sub_i32 s1, 0x400, s52
	s_min_i32 s0, s1, s0
	s_cmpk_lt_i32 s52, 0x400
	s_cselect_b32 s53, s0, 0
	s_cmp_lt_i32 s53, 1
	s_mov_b32 s1, 0
	s_cbranch_scc1 .LBB0_1409
	v_writelane_b32 v244, s30, 7
	s_and_b32 s0, s52, 31
	s_bfe_u32 s91, s52, 0x10005
	v_writelane_b32 v244, s31, 8
	s_min_u32 s39, s0, 29
	s_lshl_b32 s8, s91, 8
	s_lshl_b32 s4, s91, 9
	v_readlane_b32 s6, v244, 48
	v_readlane_b32 s7, v244, 49
	s_add_u32 s6, s6, s4
	s_addc_u32 s7, s7, 0
	s_ashr_i32 s4, s52, 6
	s_ashr_i32 s5, s4, 31
	v_sub_u32_e64 v1, s0, 2 clamp
	s_lshl_b64 s[12:13], s[4:5], 11
	v_readfirstlane_b32 s82, v1
	s_lshl_b64 s[4:5], s[4:5], 19
	v_lshlrev_b32_e32 v1, 14, v1
	v_or_b32_e32 v2, s4, v1
	v_mov_b32_e32 v3, s5
	v_readlane_b32 s4, v244, 52
	v_readlane_b32 s5, v244, 53
	s_lshl_b32 s9, s0, 6
	s_lshl_b32 s0, s91, 7
	v_lshl_add_u64 v[4:5], s[4:5], 0, v[2:3]
	v_readlane_b32 s4, v244, 50
	v_readlane_b32 s5, v244, 51
	v_mov_b32_e32 v7, v0
	v_lshl_add_u64 v[4:5], v[4:5], 0, s[0:1]
	v_lshl_add_u64 v[2:3], s[4:5], 0, v[2:3]
	v_lshl_add_u64 v[2:3], v[2:3], 0, s[0:1]
	s_or_b32 s22, s12, s9
	v_readfirstlane_b32 s0, v7
	s_ashr_i32 s23, s0, 6
	s_and_b32 s92, s23, 3
	s_ashr_i32 s24, s0, 3
	s_and_b32 s4, s24, 0xffffffe0
	s_and_b32 s26, s0, 0x3fffffc0
	s_lshl_b32 s0, s92, 11
	v_bfe_u32 v13, v7, 2, 4
	s_add_i32 s0, s0, s4
	s_lshl_b32 s78, s91, 6
	v_bfe_u32 v1, v7, 4, 2
	v_lshl_add_u32 v14, v13, 7, s0
	s_lshl_b32 s0, s23, 10
	v_bitop3_b32 v12, v1, v7, 3 bitop3:0x78
	s_cmp_lg_u32 0, -1
	v_and_b32_e32 v11, 3, v7
	v_lshlrev_b32_e32 v6, 3, v12
	s_cselect_b32 s5, 0, 0
	v_or_b32_e32 v1, v14, v6
	v_lshlrev_b32_e32 v11, 3, v11
	s_add_i32 s93, s0, s5
	v_readfirstlane_b32 s15, v3
	v_readfirstlane_b32 s14, v2
	s_ashr_i32 s5, s4, 31
	v_or_b32_e32 v2, s22, v13
	v_mov_b32_e32 v3, s13
	v_lshlrev_b32_e32 v1, 1, v1
	v_or_b32_e32 v14, v14, v11
	s_nop 4
	s_mov_b32 s0, m0
	s_mov_b32 m0, s93
	s_nop 0
	global_load_lds_dwordx4 v1, s[14:15]
	s_mov_b32 m0, s0
	v_lshl_add_u64 v[2:3], v[2:3], 0, s[4:5]
	s_waitcnt lgkmcnt(0)
	v_lshlrev_b32_e32 v196, 1, v14
	s_add_i32 s94, s93, 0x6000
	v_readfirstlane_b32 s15, v5
	v_readfirstlane_b32 s14, v4
	s_nop 4
	s_mov_b32 s0, m0
	s_mov_b32 m0, s94
	s_nop 0
	global_load_lds_dwordx4 v196, s[14:15]
	s_mov_b32 m0, s0
	v_lshlrev_b64 v[2:3], 10, v[2:3]
	v_lshl_add_u64 v[2:3], s[6:7], 0, v[2:3]
	s_lshl_b32 s0, s92, 7
	v_lshl_add_u64 v[2:3], v[2:3], 0, s[0:1]
	v_mov_b32_e32 v179, 0
	v_lshlrev_b32_e32 v178, 4, v12
	v_lshl_add_u64 v[2:3], v[2:3], 0, v[178:179]
	s_movk_i32 s0, 0x4000
	v_add_co_u32_e32 v4, vcc, s0, v2
	s_mul_i32 s27, s23, 0x1800
	s_nop 0
	v_addc_co_u32_e32 v5, vcc, 0, v3, vcc
	global_load_dwordx4 v[130:133], v[2:3], off
	global_load_dwordx4 v[134:137], v[2:3], off offset:64
	global_load_dwordx4 v[138:141], v[4:5], off
	global_load_dwordx4 v[142:145], v[4:5], off offset:64
	s_lshl_b32 s0, s26, 2
	v_mov_b32_e32 v181, s5
	s_lshl_b32 s5, s23, 12
	v_and_b32_e32 v9, 31, v7
	v_bfe_u32 v10, v7, 5, 1
	v_lshlrev_b32_e32 v14, 6, v7
	s_add_i32 s0, s0, 0
	s_add_i32 s6, s27, 0
	s_add_i32 s5, s5, 0
	v_and_b32_e32 v8, 63, v7
	v_and_b32_e32 v15, 0x400, v14
	v_and_b32_e32 v14, 0x3c0, v14
	v_lshlrev_b32_e32 v16, 1, v7
	v_lshlrev_b32_e32 v17, 2, v10
	v_lshrrev_b32_e32 v18, 2, v7
	v_bfe_u32 v19, v7, 2, 2
	s_add_i32 s14, s6, 0x12800
	v_lshl_add_u32 v202, v9, 2, s0
	v_lshl_add_u32 v5, v9, 1, s5
	v_bfe_u32 v9, v7, 3, 3
	v_and_b32_e32 v16, 32, v16
	v_or_b32_e32 v19, v17, v19
	v_bitop3_b32 v18, v10, v18, 3 bitop3:0x78
	v_add3_u32 v197, 0, v15, v14
	v_cmp_gt_u32_e64 s[6:7], 32, v8
	v_lshlrev_b32_e32 v3, 4, v8
	v_add3_u32 v201, s14, v15, v14
	v_or_b32_e32 v180, s4, v13
	v_lshlrev_b32_e32 v2, 3, v7
	v_lshlrev_b32_e32 v13, 7, v9
	v_lshl_add_u32 v204, v10, 4, s0
	v_lshlrev_b32_e32 v14, 9, v10
	v_lshlrev_b32_e32 v4, 10, v9
	v_or_b32_e32 v8, 8, v9
	v_or_b32_e32 v10, 16, v9
	v_or_b32_e32 v9, 24, v9
	s_movk_i32 s25, 0xffe0
	v_add_u32_e32 v16, 0, v16
	v_lshlrev_b32_e32 v19, 6, v19
	v_lshlrev_b32_e32 v199, 4, v18
	v_and_b32_e32 v2, 56, v2
	v_lshlrev_b32_e32 v18, 7, v9
	v_lshlrev_b32_e32 v12, 10, v9
	v_mov_b32_e32 v9, s24
	s_lshl_b32 s38, s92, 6
	v_add3_u32 v198, v16, v11, v19
	v_lshl_add_u32 v11, v2, 1, s5
	v_lshlrev_b32_e32 v15, 7, v8
	v_lshlrev_b32_e32 v8, 10, v8
	v_lshlrev_b32_e32 v16, 7, v10
	v_lshlrev_b32_e32 v10, 10, v10
	v_bfi_b32 v7, s25, v9, v7
	v_add_u32_e32 v206, s14, v3
	s_mov_b32 s14, 2.0
	s_mov_b32 s36, 0x41000000
	s_mov_b32 s40, 0x41200000
	s_mov_b32 s54, 0x41800000
	s_mov_b32 s56, 0x41900000
	s_mov_b32 s42, 0x41c00000
	s_mov_b32 s44, 0x41d00000
	s_mov_b32 s46, 0x42080000
	s_mov_b32 s48, 0x42200000
	s_mov_b32 s50, 0x42280000
	s_mov_b32 s58, 0x42400000
	s_mov_b32 s60, 0x42480000
	s_mov_b32 s62, 0x42600000
	s_mov_b32 s64, 0x42680000
	v_cndmask_b32_e64 v200, 0, 1.0, s[6:7]
	v_xor_b32_e32 v203, 32, v199
	v_sub_u32_e32 v205, v7, v17
	s_sub_i32 s5, 0, s4
	s_mov_b32 s15, 0x40400000
	s_mov_b32 s37, 0x41100000
	s_mov_b32 s41, 0x41300000
	s_mov_b32 s55, 0x41880000
	s_mov_b32 s57, 0x41980000
	s_mov_b32 s43, 0x41c80000
	s_mov_b32 s45, 0x41d80000
	s_mov_b32 s95, 0x43000000
	s_mov_b32 s47, 0x420c0000
	s_mov_b32 s49, 0x42240000
	s_mov_b32 s51, 0x422c0000
	s_mov_b32 s59, 0x42440000
	s_mov_b32 s61, 0x424c0000
	s_mov_b32 s63, 0x42640000
	s_mov_b32 s65, 0x426c0000
	v_lshlrev_b32_e32 v182, 1, v6
	v_add_u32_e32 v207, v5, v14
	s_lshl_b32 s66, s38, 1
	v_lshlrev_b32_e32 v178, 1, v2
	v_add_u32_e32 v208, v11, v13
	v_lshlrev_b32_e32 v184, 1, v4
	v_add_u32_e32 v209, v11, v15
	v_lshlrev_b32_e32 v186, 1, v8
	v_add_u32_e32 v210, v11, v16
	v_lshlrev_b32_e32 v188, 1, v10
	v_add_u32_e32 v211, v11, v18
	v_lshlrev_b32_e32 v190, 1, v12
	v_mov_b32_e32 v212, 0xff800000
	s_mov_b32 s96, 0
	s_mov_b32 s97, 0
	v_readlane_b32 s98, v244, 25
	v_readlane_b32 s99, v244, 26
	s_lshl_b32 s100, s91, 2
	s_or_b32 s100, s100, s92
	s_lshl_b32 s100, s100, 2
	s_add_u32 s98, s98, s100
	s_addc_u32 s99, s99, 0
	s_nop 3
	global_load_dword v247, v179, s[98:99]
	s_waitcnt vmcnt(0)
	s_branch .LBB0_1341
.LBB0_1340:
	s_or_b64 exec, exec, s[70:71]
	v_readlane_b32 s98, v244, 25
	v_readlane_b32 s99, v244, 26
	s_lshl_b32 s100, s91, 2
	s_or_b32 s100, s100, s92
	s_lshl_b32 s100, s100, 2
	s_add_u32 s98, s98, s100
	s_addc_u32 s99, s99, 0
	s_nop 3
	global_load_dword v247, v179, s[98:99]
	ds_read_b128 v[2:5], v204 offset:41088
	ds_read_b128 v[6:9], v204 offset:41120
	s_add_i32 s0, s9, s4
	s_min_u32 s39, s38, 29
	s_ashr_i32 s9, s0, 31
	s_waitcnt lgkmcnt(1)
	v_rcp_f32_e32 v10, v2
	v_rcp_f32_e32 v11, v3
	v_rcp_f32_e32 v12, v4
	v_rcp_f32_e32 v13, v5
	v_mul_f32_e32 v18, v34, v10
	v_mul_f32_e32 v10, v50, v10
	v_cvt_pk_bf16_f32 v10, v10, s0
	ds_write_b16 v207, v10 offset:43072
	v_mul_f32_e32 v10, v35, v11
	v_cvt_pk_bf16_f32 v10, v10, s0
	ds_write_b16 v207, v10 offset:43136
	v_mul_f32_e32 v10, v51, v11
	v_cvt_pk_bf16_f32 v10, v10, s0
	ds_write_b16 v207, v10 offset:43200
	v_mul_f32_e32 v10, v36, v12
	v_cvt_pk_bf16_f32 v10, v10, s0
	ds_write_b16 v207, v10 offset:43264
	v_mul_f32_e32 v10, v52, v12
	v_cvt_pk_bf16_f32 v10, v10, s0
	s_waitcnt lgkmcnt(4)
	v_rcp_f32_e32 v14, v6
	ds_write_b16 v207, v10 offset:43328
	v_mul_f32_e32 v10, v37, v13
	v_cvt_pk_bf16_f32 v10, v10, s0
	ds_write_b16 v207, v10 offset:43392
	v_mul_f32_e32 v10, v53, v13
	v_cvt_pk_bf16_f32 v10, v10, s0
	v_rcp_f32_e32 v15, v7
	ds_write_b16 v207, v10 offset:43456
	v_mul_f32_e32 v10, v38, v14
	v_cvt_pk_bf16_f32 v10, v10, s0
	ds_write_b16 v207, v10 offset:44032
	v_mul_f32_e32 v10, v54, v14
	v_cvt_pk_bf16_f32 v10, v10, s0
	v_rcp_f32_e32 v16, v8
	ds_write_b16 v207, v10 offset:44096
	v_mul_f32_e32 v10, v39, v15
	v_cvt_pk_bf16_f32 v10, v10, s0
	ds_write_b16 v207, v10 offset:44160
	v_mul_f32_e32 v10, v55, v15
	ds_read_b128 v[2:5], v204 offset:41152
	v_cvt_pk_bf16_f32 v10, v10, s0
	v_rcp_f32_e32 v17, v9
	ds_write_b16 v207, v10 offset:44224
	v_mul_f32_e32 v10, v40, v16
	v_cvt_pk_bf16_f32 v10, v10, s0
	ds_write_b16 v207, v10 offset:44288
	v_mul_f32_e32 v10, v56, v16
	v_cvt_pk_bf16_f32 v10, v10, s0
	ds_read_b128 v[6:9], v204 offset:41184
	s_waitcnt lgkmcnt(3)
	v_rcp_f32_e32 v2, v2
	ds_write_b16 v207, v10 offset:44352
	v_mul_f32_e32 v10, v41, v17
	v_cvt_pk_bf16_f32 v10, v10, s0
	v_rcp_f32_e32 v3, v3
	ds_write_b16 v207, v10 offset:44416
	v_mul_f32_e32 v10, v57, v17
	v_cvt_pk_bf16_f32 v10, v10, s0
	ds_write_b16 v207, v10 offset:44480
	v_mul_f32_e32 v10, v42, v2
	v_mul_f32_e32 v2, v58, v2
	v_cvt_pk_bf16_f32 v2, v2, s0
	v_rcp_f32_e32 v4, v4
	ds_write_b16 v207, v2 offset:45120
	v_mul_f32_e32 v2, v43, v3
	v_cvt_pk_bf16_f32 v2, v2, s0
	ds_write_b16 v207, v2 offset:45184
	v_mul_f32_e32 v2, v59, v3
	v_cvt_pk_bf16_f32 v2, v2, s0
	v_rcp_f32_e32 v5, v5
	ds_write_b16 v207, v2 offset:45248
	v_mul_f32_e32 v2, v44, v4
	v_cvt_pk_bf16_f32 v2, v2, s0
	ds_write_b16 v207, v2 offset:45312
	v_mul_f32_e32 v2, v60, v4
	v_cvt_pk_bf16_f32 v2, v2, s0
	s_waitcnt lgkmcnt(7)
	v_rcp_f32_e32 v6, v6
	ds_write_b16 v207, v2 offset:45376
	v_mul_f32_e32 v2, v45, v5
	v_cvt_pk_bf16_f32 v2, v2, s0
	ds_write_b16 v207, v2 offset:45440
	v_mul_f32_e32 v2, v61, v5
	v_cvt_pk_bf16_f32 v2, v2, s0
	v_rcp_f32_e32 v7, v7
	ds_write_b16 v207, v2 offset:45504
	v_mul_f32_e32 v2, v46, v6
	v_cvt_pk_bf16_f32 v2, v2, s0
	ds_write_b16 v207, v2 offset:46080
	v_mul_f32_e32 v2, v62, v6
	v_cvt_pk_bf16_f32 v2, v2, s0
	v_rcp_f32_e32 v8, v8
	ds_write_b16 v207, v2 offset:46144
	v_mul_f32_e32 v2, v47, v7
	v_cvt_pk_bf16_f32 v2, v2, s0
	ds_write_b16 v207, v2 offset:46208
	v_mul_f32_e32 v2, v63, v7
	v_cvt_pk_bf16_f32 v2, v2, s0
	v_rcp_f32_e32 v9, v9
	ds_write_b16 v207, v2 offset:46272
	v_mul_f32_e32 v2, v48, v8
	v_cvt_pk_bf16_f32 v2, v2, s0
	ds_write_b16 v207, v2 offset:46336
	v_mul_f32_e32 v2, v64, v8
	v_cvt_pk_bf16_f32 v2, v2, s0
	ds_write_b16 v207, v2 offset:46400
	v_mul_f32_e32 v2, v49, v9
	s_add_u32 s12, s12, s0
	v_cvt_pk_bf16_f32 v2, v2, s0
	s_addc_u32 s13, s13, s9
	ds_write_b16 v207, v2 offset:46464
	v_mul_f32_e32 v2, v65, v9
	s_lshl_b64 s[12:13], s[12:13], 11
	v_cvt_pk_bf16_f32 v18, v18, s0
	v_cvt_pk_bf16_f32 v10, v10, s0
	v_cvt_pk_bf16_f32 v2, v2, s0
	s_add_u32 s0, s3, s12
	s_mov_b32 s9, s1
	s_addc_u32 s12, s90, s13
	s_lshl_b64 s[8:9], s[8:9], 1
	ds_write_b16 v207, v18 offset:43008
	s_add_u32 s0, s0, s8
	ds_write_b16 v207, v2 offset:46528
	s_addc_u32 s9, s12, s9
	ds_read_b128 v[2:5], v208 offset:43008
	ds_read_b128 v[6:9], v209 offset:43008
	s_add_u32 s8, s0, s66
	s_addc_u32 s9, s9, 0
	ds_write_b16 v207, v10 offset:45056
	v_lshl_add_u64 v[10:11], s[8:9], 0, v[178:179]
	v_mov_b32_e32 v185, v179
	v_lshl_add_u64 v[12:13], v[10:11], 0, v[184:185]
	v_mov_b32_e32 v187, v179
	s_waitcnt lgkmcnt(2)
	s_waitcnt vmcnt(0)
	global_store_dwordx4 v[12:13], v[2:5], off offset:1024
	v_lshl_add_u64 v[12:13], v[10:11], 0, v[186:187]
	ds_read_b128 v[2:5], v210 offset:43008
	s_waitcnt lgkmcnt(2)
	global_store_dwordx4 v[12:13], v[6:9], off offset:1024
	ds_read_b128 v[6:9], v211 offset:43008
	v_mov_b32_e32 v189, v179
	v_lshl_add_u64 v[12:13], v[10:11], 0, v[188:189]
	v_mov_b32_e32 v191, v179
	s_waitcnt lgkmcnt(1)
	global_store_dwordx4 v[12:13], v[2:5], off offset:1024
	s_cmp_lg_u32 s97, s53
	s_mov_b32 s78, s68
	v_lshl_add_u64 v[2:3], v[10:11], 0, v[190:191]
	s_mov_b32 s8, s75
	s_mov_b32 s82, s69
	s_mov_b32 s9, s74
	s_mov_b64 s[12:13], s[72:73]
	s_waitcnt lgkmcnt(0)
	global_store_dwordx4 v[2:3], v[6:9], off offset:1024
	s_cbranch_scc0 .LBB0_1408
.LBB0_1341:
	s_lshl_b32 s0, s91, 2
	s_mov_b32 s38, s97
	s_add_i32 s97, s97, 1
	s_cmp_lt_u32 s97, s53
	s_cselect_b64 s[70:71], -1, 0
	s_and_b64 s[68:69], s[70:71], exec
	s_cselect_b32 s38, s97, s38
	s_add_i32 s67, s38, s52
	s_bfe_u32 s91, s67, 0x10005
	s_ashr_i32 s72, s67, 6
	s_or_b32 s0, s0, s92
	v_readlane_b32 s16, v244, 23
	s_and_b32 s38, s67, 31
	s_ashr_i32 s73, s72, 31
	s_lshl_b32 s68, s91, 6
	s_lshl_b64 s[74:75], s[0:1], 2
	v_readlane_b32 s18, v244, 25
	v_readlane_b32 s19, v244, 26
	s_add_u32 s74, s18, s74
	s_addc_u32 s75, s19, s75
	v_add_u32_e32 v3, v201, v199
	v_add_u32_e32 v4, v201, v203
	s_add_i32 s39, s39, 3
	s_cmp_ge_i32 s82, s39
	v_readlane_b32 s17, v244, 24
	v_readlane_b32 s20, v244, 27
	v_readlane_b32 s21, v244, 28
	v_readlane_b32 s22, v244, 29
	v_readlane_b32 s23, v244, 30
	v_readlane_b32 s24, v244, 31
	v_readlane_b32 s25, v244, 32
	v_readlane_b32 s26, v244, 33
	v_readlane_b32 s27, v244, 34
	v_readlane_b32 s28, v244, 35
	v_readlane_b32 s29, v244, 36
	v_readlane_b32 s30, v244, 37
	v_readlane_b32 s31, v244, 38
	v_mov_b32_e32 v2, v247
	v_mul_f32_e32 v187, 0x3fb8aa3b, v2
	v_xor_b32_e32 v66, 0x80000000, v187
	v_mov_b32_e32 v67, v66
	v_mov_b32_e32 v68, v66
	v_mov_b32_e32 v69, v66
	v_mov_b32_e32 v70, v66
	v_mov_b32_e32 v71, v66
	v_mov_b32_e32 v72, v66
	v_mov_b32_e32 v73, v66
	v_mov_b32_e32 v74, v66
	v_mov_b32_e32 v75, v66
	v_mov_b32_e32 v76, v66
	v_mov_b32_e32 v77, v66
	v_mov_b32_e32 v78, v66
	v_mov_b32_e32 v79, v66
	v_mov_b32_e32 v80, v66
	v_mov_b32_e32 v81, v66
	s_waitcnt lgkmcnt(0)
	s_barrier
	ds_write_b128 v206, v[130:133]
	ds_write_b128 v206, v[138:141] offset:1024
	ds_write_b128 v206, v[134:137] offset:2048
	ds_write_b128 v206, v[142:145] offset:3072
	ds_read_b128 v[130:133], v3
	ds_read_b128 v[134:137], v3 offset:2048
	ds_read_b128 v[138:141], v4
	ds_read_b128 v[142:145], v4 offset:2048
	v_sub_u32_e64 v2, s38, 2 clamp
	s_nop 0
	v_readfirstlane_b32 s69, v2
	s_cbranch_scc1 .LBB0_1402
	s_add_i32 s0, s0, 1
	v_cvt_f32_u32_e32 v2, s0
	s_lshl_b32 s0, s69, 14
	s_lshl_b64 s[76:77], s[72:73], 19
	s_or_b32 s0, s76, s0
	v_readlane_b32 s16, v244, 50
	v_readlane_b32 s17, v244, 51
	s_add_u32 s67, s16, s0
	s_addc_u32 s75, s17, s77
	s_lshl_b32 s76, s68, 1
	s_add_u32 s74, s67, s76
	s_addc_u32 s75, s75, 0
	v_readlane_b32 s18, v244, 52
	v_readlane_b32 s19, v244, 53
	s_add_u32 s0, s18, s0
	s_addc_u32 s67, s19, s77
	s_add_u32 s76, s0, s76
	s_mov_b32 s79, s1
	s_addc_u32 s77, s67, 0
	s_lshl_b64 s[78:79], s[78:79], 1
	s_add_u32 s0, s16, s78
	s_addc_u32 s67, s17, s79
	s_add_u32 s84, s18, s78
	s_addc_u32 s85, s19, s79
	s_ashr_i32 s83, s82, 31
	s_lshl_b64 s[78:79], s[82:83], 14
	s_lshl_b64 s[80:81], s[12:13], 8
	s_add_u32 s80, s78, s80
	s_addc_u32 s81, s79, s81
	s_add_u32 s78, s84, s80
	s_addc_u32 s79, s85, s81
	s_add_u32 s78, s78, 0x4000
	v_exp_f32_e64 v2, -v2
	s_addc_u32 s79, s79, 0
	s_add_u32 s0, s0, s80
	s_addc_u32 s67, s67, s81
	s_add_u32 s80, s0, 0x4000
	v_mul_f32_e32 v192, 0xbfb8aa3b, v2
	s_addc_u32 s81, s67, 0
	v_add_u32_e32 v2, s9, v205
	s_lshl_b32 s0, s82, 6
	v_subrev_u32_e32 v183, s0, v2
	s_add_i32 s0, s5, s0
	v_mov_b32_e32 v194, v192
	v_mov_b32_e32 v195, v192
	s_sub_i32 s0, s0, s9
	v_mov_b32_e32 v2, v179
	v_mov_b32_e32 v3, v179
	v_mov_b32_e32 v4, v179
	v_mov_b32_e32 v5, v179
	v_mov_b32_e32 v6, v179
	v_mov_b32_e32 v7, v179
	v_mov_b32_e32 v8, v179
	v_mov_b32_e32 v9, v179
	v_mov_b32_e32 v10, v179
	v_mov_b32_e32 v11, v179
	v_mov_b32_e32 v12, v179
	v_mov_b32_e32 v13, v179
	v_mov_b32_e32 v14, v179
	v_mov_b32_e32 v15, v179
	v_mov_b32_e32 v16, v179
	v_mov_b32_e32 v17, v179
	v_mov_b32_e32 v18, v179
	v_mov_b32_e32 v19, v179
	v_mov_b32_e32 v20, v179
	v_mov_b32_e32 v21, v179
	v_mov_b32_e32 v22, v179
	v_mov_b32_e32 v23, v179
	v_mov_b32_e32 v24, v179
	v_mov_b32_e32 v25, v179
	v_mov_b32_e32 v26, v179
	v_mov_b32_e32 v27, v179
	v_mov_b32_e32 v28, v179
	v_mov_b32_e32 v29, v179
	v_mov_b32_e32 v30, v179
	v_mov_b32_e32 v31, v179
	v_mov_b32_e32 v32, v179
	v_mov_b32_e32 v33, v179
	v_mov_b32_e32 v185, v200
